# conversion engine v10: transposed stores also issued at the end of load segment 1 (3-phase completion window)
# baseline (speedup 1.0000x reference)
; #define GAS __attribute__((address_space(1)))
; #define LAS __attribute__((address_space(3)))
; __device__ __forceinline__ void conv_store(const ConvItem& it, int lane, const f32x4 (&v)[4], LAS bf16* scr) {
;     ...
;     const int c = lane & 3;
; #pragma unroll
;     for (int j = 0; j < 2; ++j) { const int n = (lane >> 2) + 16 * j; const LAS bf16* sp = scr + (8 * c) * 34 + n;
;         v4u o; o.x = (unsigned)sp[0] | ((unsigned)sp[34] << 16); o.y = (unsigned)sp[68] | ((unsigned)sp[102] << 16); o.z = (unsigned)sp[136] | ((unsigned)sp[170] << 16); o.w = (unsigned)sp[204] | ((unsigned)sp[238] << 16);
;         const int ng = it.n0 + n; const int row = it.rowmode == 0 ? ng : ((ng >> 7) * 256 + (it.rowmode == 2 ? 128 : 0) + (ng & 127));
;         __builtin_nontemporal_store(o, (GAS v4u*)(it.WT + (size_t)row * it.ldt + it.k0 + 8 * c)); }
.Leng_st3:
	v_and_b32_e32 v254, 3, v1
	v_lshlrev_b32_e32 v254, 4, v254
	v_lshrrev_b32_e32 v255, 2, v1
	v_lshl_add_u32 v254, v255, 13, v254
	v_add_u32_e32 v255, 0x20000, v254
	v_lshl_or_b32 v232, v233, 16, v232
	v_lshl_or_b32 v233, v235, 16, v234
	v_lshl_or_b32 v234, v237, 16, v236
	v_lshl_or_b32 v235, v239, 16, v238
	v_lshl_or_b32 v236, v241, 16, v240
	v_lshl_or_b32 v237, v243, 16, v242
	v_lshl_or_b32 v238, v247, 16, v246
	v_lshl_or_b32 v239, v249, 16, v248
	s_and_b32 s98, s100, -2
	s_mov_b32 s99, s101
	s_mov_b32 s97, 2

; #define PG8_STAGE(bufoff, gbase, voff) do { _Pragma("unroll") for (int _i = 0; _i < 2; ++_i) \
;         __builtin_amdgcn_global_load_lds((const unsigned*)((const char*)(gbase) + (voff)[_i]), (PG8_LAS unsigned*)(lds + (bufoff) + ldsw + _i * 8192), 16, 0, 0); } while (0)
; #define PG8_LDA(dst, b, h) do { _Pragma("unroll") for (int m = 0; m < 4; ++m) _Pragma("unroll") for (int k = 0; k < 2; ++k) dst[m][k] = *(const PG8_LAS bf16x8*)(lds + PG8_SA(b, h) + aoff + m * 2048 + k * 1024); } while (0)
; #define PG8_LDB(dst, b, h) do { _Pragma("unroll") for (int n = 0; n < 2; ++n) _Pragma("unroll") for (int k = 0; k < 2; ++k) dst[n][k] = *(const PG8_LAS bf16x8*)(lds + PG8_SB(b, h) + boff + n * 2048 + k * 1024); } while (0)
; #define PG8_SCHED __builtin_amdgcn_sched_barrier(0)
; #define GAS __attribute__((address_space(1)))
; template <class Epi, class Sched, bool ALIGN_EPI = false, bool SP2 = false>
; __device__ __forceinline__ void gemm_phase(PG8_LAS unsigned char* lds, const Gemm g, const Sched& S, const Epi& E) {
;     ...
;             PG8_LDB(B0, 0, 0); PG8_LDB(B1, 0, 1); PG8_SCHED; PG8_LDA(At, 0, 0); PG8_STAGE(PG8_SA(1, 1), a1 + hstepA, voffA);
; __device__ __forceinline__ void conv_store(const ConvItem& it, int lane, const f32x4 (&v)[4], LAS bf16* scr) {
;     ...
;         const int ng = it.n0 + n; const int row = it.rowmode == 0 ? ng : ((ng >> 7) * 256 + (it.rowmode == 2 ? 128 : 0) + (ng & 127));
;         __builtin_nontemporal_store(o, (GAS v4u*)(it.WT + (size_t)row * it.ldt + it.k0 + 8 * c)); }
.Leng_done:
	ds_read_b128 v[130:133], v167
	ds_read_b128 v[134:137], v167 offset:1024
	ds_read_b128 v[156:159], v167 offset:2048
	ds_read_b128 v[172:175], v167 offset:3072
	ds_read_b128 v[176:179], v168
	ds_read_b128 v[180:183], v168 offset:1024
	ds_read_b128 v[184:187], v168 offset:2048
	ds_read_b128 v[188:191], v168 offset:3072
	s_add_u32 s8, s6, 0xfff00080
	s_addc_u32 s9, s7, -1
	s_cmp_eq_u32 s45, 60
	s_cselect_b32 s37, s1, s9
	s_cselect_b32 s36, s14, s8
	s_cselect_b32 s9, s25, s44
	s_cselect_b32 s8, s27, s33
	v_lshl_add_u64 v[160:161], s[6:7], 0, v[148:149]
	s_add_i32 m0, s55, 0xc000
	ds_read_b128 v[192:195], v169
	ds_read_b128 v[196:199], v169 offset:1024
	ds_read_b128 v[200:203], v169 offset:2048
	ds_read_b128 v[204:207], v169 offset:3072
	ds_read_b128 v[208:211], v169 offset:4096
	ds_read_b128 v[212:215], v169 offset:5120
	ds_read_b128 v[216:219], v169 offset:6144
	ds_read_b128 v[220:223], v169 offset:7168
	global_load_lds_dwordx4 v[160:161], off
	v_lshl_add_u64 v[160:161], s[6:7], 0, v[150:151]
	s_add_i32 m0, s55, 0xe000
	s_nop 0
	global_load_lds_dwordx4 v[160:161], off
	s_cmp_eq_u32 s97, 2
	s_cbranch_scc0 .Leng_st_skip
	global_store_dwordx4 v254, v[232:235], s[98:99] nt
	global_store_dwordx4 v255, v[236:239], s[98:99] nt
.Leng_st_skip:
	s_cmp_lt_u32 s97, 4
	s_cbranch_scc1 .Leng_ld_done
	v_lshrrev_b32_e32 v254, 3, v1
	v_and_b32_e32 v255, 7, v1
	s_cmp_eq_u32 s97, 8
	s_cbranch_scc0 .Leng_ldB
	v_mul_u32_u24_e32 v254, 0xac00, v254
	v_lshl_add_u32 v254, v255, 4, v254
	global_load_dwordx4 v[232:235], v254, s[98:99] nt
	s_add_u32 s98, s98, 0x56000
	s_addc_u32 s99, s99, 0
	global_load_dwordx4 v[236:239], v254, s[98:99] nt
	s_add_u32 s98, s98, 0x56000
	s_addc_u32 s99, s99, 0
	global_load_dwordx4 v[240:243], v254, s[98:99] nt
	s_add_u32 s98, s98, 0x56000
	s_addc_u32 s99, s99, 0
	global_load_dwordx4 v[246:249], v254, s[98:99] nt
	v_readlane_b32 s98, v245, 4
	v_readlane_b32 s99, v245, 5
	v_lshrrev_b32_e32 v255, 3, v1
	v_lshlrev_b32_e32 v255, 2, v255
	s_lshl_b32 s93, s93, 7
	s_nop 1
	s_add_u32 s98, s98, s93
	s_addc_u32 s99, s99, 0
	global_load_dword v250, v255, s[98:99]
	global_load_dword v251, v255, s[98:99] offset:32
	global_load_dword v252, v255, s[98:99] offset:64
	global_load_dword v253, v255, s[98:99] offset:96
	s_branch .Leng_ld_done

; #define PG8_STAGE(bufoff, gbase, voff) do { _Pragma("unroll") for (int _i = 0; _i < 2; ++_i) \
;         __builtin_amdgcn_global_load_lds((const unsigned*)((const char*)(gbase) + (voff)[_i]), (PG8_LAS unsigned*)(lds + (bufoff) + ldsw + _i * 8192), 16, 0, 0); } while (0)
; #define PG8_LDA(dst, b, h) do { _Pragma("unroll") for (int m = 0; m < 4; ++m) _Pragma("unroll") for (int k = 0; k < 2; ++k) dst[m][k] = *(const PG8_LAS bf16x8*)(lds + PG8_SA(b, h) + aoff + m * 2048 + k * 1024); } while (0)
; #define PG8_LDB(dst, b, h) do { _Pragma("unroll") for (int n = 0; n < 2; ++n) _Pragma("unroll") for (int k = 0; k < 2; ++k) dst[n][k] = *(const PG8_LAS bf16x8*)(lds + PG8_SB(b, h) + boff + n * 2048 + k * 1024); } while (0)
; #define PG8_MMA(ai, bj, At, Bt) do { __builtin_amdgcn_s_setprio(3); _Pragma("unroll") for (int m = 0; m < 4; ++m) _Pragma("unroll") for (int n = 0; n < 2; ++n) _Pragma("unroll") for (int k = 0; k < 2; ++k) \
;         acc[ai][bj][m][n] = __builtin_amdgcn_mfma_f32_16x16x32_bf16(Bt[n][k], At[m][k], acc[ai][bj][m][n], 0, 0, 0); __builtin_amdgcn_s_setprio(0); } while (0)
; #define PG8_WAIT_V(n) asm volatile("s_waitcnt vmcnt(" #n ")" ::: "memory")
; #define PG8_WAIT_L(n) asm volatile("s_waitcnt lgkmcnt(" #n ")" ::: "memory")
; #define PG8_BAR __builtin_amdgcn_s_barrier()
; #define PG8_SCHED __builtin_amdgcn_sched_barrier(0)
; template <class Epi, class Sched, bool ALIGN_EPI = false, bool SP2 = false>
; __device__ __forceinline__ void gemm_phase(PG8_LAS unsigned char* lds, const Gemm g, const Sched& S, const Epi& E) {
;     ...
;             PG8_WAIT_V(8); PG8_WAIT_L(0); PG8_BAR; PG8_MMA(1, 0, At, B0); PG8_MMA(1, 1, At, B1); PG8_BAR; PG8_SCHED;
;             PG8_LDB(B0, 1, 0); PG8_LDB(B1, 1, 1); PG8_SCHED; PG8_LDA(At, 1, 0); PG8_STAGE(PG8_SA(0, 1), a2 + hstepA, voffA);
;             PG8_WAIT_V(8); PG8_WAIT_L(0); PG8_BAR; PG8_MMA(0, 0, At, B0); PG8_MMA(0, 1, At, B1); PG8_BAR; PG8_SCHED;
.Lengw2_e:
	s_waitcnt lgkmcnt(0)
	s_barrier
	s_setprio 3
	s_waitcnt lgkmcnt(0)
	v_mfma_f32_16x16x32_bf16 v[62:65], v[130:133], v[192:195], v[62:65]
	v_mfma_f32_16x16x32_bf16 v[54:57], v[156:159], v[192:195], v[54:57]
	v_mfma_f32_16x16x32_bf16 v[46:49], v[130:133], v[200:203], v[46:49]
	v_mfma_f32_16x16x32_bf16 v[38:41], v[156:159], v[200:203], v[38:41]
	v_mfma_f32_16x16x32_bf16 v[30:33], v[130:133], v[208:211], v[30:33]
	v_mfma_f32_16x16x32_bf16 v[22:25], v[156:159], v[208:211], v[22:25]
	v_mfma_f32_16x16x32_bf16 v[14:17], v[130:133], v[216:219], v[14:17]
	v_mfma_f32_16x16x32_bf16 v[6:9], v[156:159], v[216:219], v[6:9]
	v_mfma_f32_16x16x32_bf16 v[62:65], v[134:137], v[196:199], v[62:65]
	v_mfma_f32_16x16x32_bf16 v[54:57], v[172:175], v[196:199], v[54:57]
	v_mfma_f32_16x16x32_bf16 v[46:49], v[134:137], v[204:207], v[46:49]
	v_mfma_f32_16x16x32_bf16 v[38:41], v[172:175], v[204:207], v[38:41]
	v_mfma_f32_16x16x32_bf16 v[30:33], v[134:137], v[212:215], v[30:33]
	v_mfma_f32_16x16x32_bf16 v[22:25], v[172:175], v[212:215], v[22:25]
	v_mfma_f32_16x16x32_bf16 v[14:17], v[134:137], v[220:223], v[14:17]
	v_mfma_f32_16x16x32_bf16 v[6:9], v[172:175], v[220:223], v[6:9]
	s_setprio 0
	s_setprio 3
	v_mfma_f32_16x16x32_bf16 v[58:61], v[176:179], v[192:195], v[58:61]
	v_mfma_f32_16x16x32_bf16 v[50:53], v[184:187], v[192:195], v[50:53]
	v_mfma_f32_16x16x32_bf16 v[42:45], v[176:179], v[200:203], v[42:45]
	v_mfma_f32_16x16x32_bf16 v[34:37], v[184:187], v[200:203], v[34:37]
	v_mfma_f32_16x16x32_bf16 v[26:29], v[176:179], v[208:211], v[26:29]
	v_mfma_f32_16x16x32_bf16 v[18:21], v[184:187], v[208:211], v[18:21]
	v_mfma_f32_16x16x32_bf16 v[10:13], v[176:179], v[216:219], v[10:13]
	v_mfma_f32_16x16x32_bf16 v[2:5], v[184:187], v[216:219], v[2:5]
	v_mfma_f32_16x16x32_bf16 v[58:61], v[180:183], v[196:199], v[58:61]
	v_mfma_f32_16x16x32_bf16 v[50:53], v[188:191], v[196:199], v[50:53]
	v_mfma_f32_16x16x32_bf16 v[42:45], v[180:183], v[204:207], v[42:45]
	v_mfma_f32_16x16x32_bf16 v[34:37], v[188:191], v[204:207], v[34:37]
	v_mfma_f32_16x16x32_bf16 v[26:29], v[180:183], v[212:215], v[26:29]
	v_mfma_f32_16x16x32_bf16 v[18:21], v[188:191], v[212:215], v[18:21]
	v_mfma_f32_16x16x32_bf16 v[10:13], v[180:183], v[220:223], v[10:13]
	v_mfma_f32_16x16x32_bf16 v[2:5], v[188:191], v[220:223], v[2:5]
	s_setprio 0
	s_barrier
	s_add_i32 s56, 0, 0x18000
	v_add_u32_e32 v146, s56, v164
	s_add_i32 s57, 0, 0x1c000
	ds_read_b128 v[130:133], v146
	ds_read_b128 v[134:137], v146 offset:1024
	ds_read_b128 v[156:159], v146 offset:2048
	ds_read_b128 v[172:175], v146 offset:3072
	v_add_u32_e32 v146, s57, v164
	ds_read_b128 v[176:179], v146
	ds_read_b128 v[180:183], v146 offset:1024
	ds_read_b128 v[184:187], v146 offset:2048
	ds_read_b128 v[188:191], v146 offset:3072
	s_add_u32 s36, s36, 0x100000
	s_addc_u32 s37, s37, 0
	s_mov_b32 m0, s72
	v_lshl_add_u64 v[230:231], s[36:37], 0, v[138:139]
	ds_read_b128 v[192:195], v169 offset:32768
	ds_read_b128 v[196:199], v169 offset:33792
	ds_read_b128 v[200:203], v169 offset:34816
	ds_read_b128 v[204:207], v169 offset:35840
	ds_read_b128 v[208:211], v169 offset:36864
	ds_read_b128 v[212:215], v169 offset:37888
	ds_read_b128 v[216:219], v169 offset:38912
	ds_read_b128 v[220:223], v169 offset:39936
	global_load_lds_dwordx4 v[230:231], off
	v_lshl_add_u64 v[230:231], s[36:37], 0, v[142:143]
	s_mov_b32 m0, s73
	s_nop 0
	global_load_lds_dwordx4 v[230:231], off
	s_cmp_eq_u32 s97, 4
	s_cbranch_scc1 .Lengw3_c
	s_cmp_eq_u32 s97, 8
	s_cbranch_scc1 .Lengw3_d
	s_cmp_eq_u32 s97, 2
	s_cbranch_scc1 .Lengw3_b
	s_waitcnt vmcnt(8)
	s_branch .Lengw3_e
.Lengw3_b:
	s_waitcnt vmcnt(10)
	s_branch .Lengw3_e
.Lengw3_c:
	s_waitcnt vmcnt(12)
	s_branch .Lengw3_e
